# weight-conversion items: S5-chain workgroups take 14 items per wave and the others 16.75 (opposite skew)
# speedup vs baseline: 1.0019x; 1.0019x over previous
; #define LAS __attribute__((address_space(3)))
; #define FRESH_IDS() int tid_ = threadIdx.x; asm volatile("" : "+v"(tid_)); const int lane = tid_ & 63; const int gt = bx * (NWAVES * 64) + tid_; (void)lane; (void)gt
; __device__ __forceinline__ void transpose_item(const float* __restrict__ W, int N, bf16* __restrict__ WT, int ld, int koff, int HG, LAS float* scr, int item, int lane) {
;     const int nblk = N / 32, kb = item / nblk, nb = item % nblk, k0 = 64 * kb, n0 = 32 * nb;
;     { f32x4 v[8]; const int kr = lane >> 3, n4 = (lane & 7) * 4;
; #pragma unroll
;       for (int i = 0; i < 8; ++i) v[i] = *(const f32x4*)(W + (size_t)(k0 + kr + 8 * i) * N + n0 + n4);
; #pragma unroll
;       for (int i = 0; i < 8; ++i) { LAS float* d = scr + (kr + 8 * i) * 33 + n4; d[0] = v[i][0]; d[1] = v[i][1]; d[2] = v[i][2]; d[3] = v[i][3]; } }
;     asm volatile("s_waitcnt lgkmcnt(0)" ::: "memory");
;     const int c = lane & 7;
; #pragma unroll
;     for (int j = 0; j < 4; ++j) { const int n = (lane >> 3) + 8 * j; const LAS float* s = scr + (8 * c) * 33 + n;
; __global__ void __launch_bounds__(NWAVES * 64, 2) hybrid_fwd(Args args) {
;     ...
;             if (pass == par) { if (conv_on) { FRESH_IDS();
;             const float* w_inc = args.in[2] + (size_t)lc * DM * INW;
;             LAS float* scr = (LAS float*)(lds + wave * 16384);
;             constexpr int I_IN = (DM / 64) * (INW / 32), I_SB = (SBW / 64) * (DM / 32), I_SS = (SSMW / 64) * (DM / 32), I_MM = (MEMW / 64) * (DM / 32), I_GL = (SSMW / 64) * (1024 / 32),
;                           I_O = (DM / 64) * (DM / 32), I_GU = (DM / 64) * (2 * DFF / 32), I_DN = (DFF / 64) * (DM / 32);
;             constexpr int NITEMS = I_IN + I_SB + I_SS + I_MM + I_GL + I_O + I_GU + I_DN;
;             for (int it = gw; it < NITEMS; it += NGW) {
;                 int r = it; const float* W; bf16* WT; int N, ld, koff = 0, HG = 0;
;                 if (r < I_IN) { W = w_inc; N = INW; WT = NXT(BT_IN); ld = DM; }
.LBB0_442:
	s_and_b64 vcc, exec, s[2:3]
	s_cbranch_vccz .LBB0_568
	v_readlane_b32 s2, v254, 25
	v_readlane_b32 s3, v254, 26
	s_and_b64 vcc, exec, s[2:3]
	s_cbranch_vccz .LBB0_568
	v_readlane_b32 s0, v251, 56
	v_readlane_b32 s1, v251, 57
	s_waitcnt vmcnt(0)
	v_mov_b32_e32 v21, v0
	s_andn2_b64 vcc, exec, s[0:1]
	s_cbranch_vccnz .LBB0_512
	v_bfe_u32 v14, v21, 3, 3
	v_and_b32_e32 v3, 7, v21
	v_readlane_b32 s0, v251, 54
	v_lshlrev_b32_e32 v2, 2, v3
	v_mul_u32_u24_e32 v6, 0x84, v14
	v_lshl_add_u32 v5, v3, 4, s0
	v_lshlrev_b32_e32 v4, 3, v3
	v_mul_u32_u24_e32 v3, 0x420, v3
	v_lshlrev_b32_e32 v7, 2, v14
	v_or_b32_e32 v15, 8, v14
	v_or_b32_e32 v16, 16, v14
	v_or_b32_e32 v17, 24, v14
	v_add3_u32 v18, s0, v3, v7
	v_lshlrev_b32_e32 v98, 2, v2
	v_add_u32_e32 v19, v5, v6
	v_lshlrev_b32_e32 v2, 1, v4
	v_readlane_b32 s10, v249, 41
	s_mov_b32 s100, 0x37ff
	s_cmpk_lt_u32 s10, 0x400
	s_cbranch_scc1 .Lcv_s5share
	s_addk_i32 s10, 0x3400
	s_movk_i32 s100, 0x7aff
